# r48 layout variant: NSA + GDN-scan unit code shifted by 4 bytes, merge/out-proj code at +8 vs r48 (code alignment tuning)
# speedup vs baseline: 1.0020x; 1.0020x over previous
.LBB0_668:
	s_or_b64 exec, exec, s[0:1]
	v_readlane_b32 s4, v251, 0
	s_lshl_b64 s[0:1], s[52:53], 2
	v_readlane_b32 s16, v251, 12
	v_readlane_b32 s17, v251, 13
	s_add_u32 s0, s16, s0
	s_addc_u32 s1, s17, s1
	v_writelane_b32 v254, s0, 27
	s_mov_b32 s41, 0
	v_readlane_b32 s5, v251, 1
	v_writelane_b32 v254, s1, 28
	v_readlane_b32 s6, v251, 2
	v_readlane_b32 s7, v251, 3
	v_readlane_b32 s8, v251, 4
	v_readlane_b32 s9, v251, 5
	v_readlane_b32 s10, v251, 6
	v_readlane_b32 s11, v251, 7
	v_readlane_b32 s12, v251, 8
	v_readlane_b32 s13, v251, 9
	v_readlane_b32 s14, v251, 10
	v_readlane_b32 s15, v251, 11
	v_readlane_b32 s18, v251, 14
	v_readlane_b32 s19, v251, 15
	s_barrier
	s_branch .LBB0_672
	s_nop 0

.LBB0_967:
	v_ashrrev_i32_e32 v5, 3, v4
	s_lshl_b64 s[6:7], s[2:3], 11
	v_add_u32_e32 v6, 64, v5
	v_mov_b32_e32 v7, v0
	v_lshl_add_u64 v[6:7], s[6:7], 0, v[6:7]
	s_waitcnt vmcnt(2)
	v_mov_b64_e32 v[8:9], s[58:59]
	s_movk_i32 s8, 0x1e00
	v_mad_u64_u32 v[8:9], s[6:7], v6, s8, v[8:9]
	v_mad_i32_i24 v9, v7, s8, v9
	s_lshl_b32 s88, s30, 7
	v_lshlrev_b32_e32 v5, 4, v2
	v_lshl_add_u64 v[6:7], v[8:9], 0, s[88:89]
	v_and_b32_e32 v8, 0x70, v5
	v_mov_b32_e32 v9, v0
	v_lshl_add_u64 v[6:7], v[6:7], 0, v[8:9]
	global_load_dwordx4 v[140:143], v[6:7], off offset:1536
	s_or_b64 exec, exec, s[4:5]
	s_and_saveexec_b64 s[4:5], s[20:21]
	s_cbranch_execnz .LBB0_903
	s_branch .LBB0_904
	s_nop 0
	s_nop 0
	s_nop 0
	s_nop 0
	s_nop 0
	s_nop 0
	s_nop 0
	s_nop 0
	s_nop 0
	s_nop 0
